# v33 + nt hint on hgC's once-read og gate columns (written in P1)
# baseline (speedup 1.0000x reference)
; __device__ __forceinline__ void hgC_loop(Frame& F, unsigned* ctr) {
;     ...
;     int item = slot[0], nxt = slot[1], par = 0;
;     if (item >= 1024) return;
;     v4u sc[4], qh[2], oi[2]; v2u og[4];
;     ...
;     HGC_FETCH(item);
.LBB0_690:
	s_or_b64 exec, exec, s[0:1]
	v_mov_b32_e32 v55, 0
	s_waitcnt lgkmcnt(0)
	s_barrier
	ds_read_b32 v2, v55 offset:53248
	ds_read_b32 v3, v55 offset:53252
	s_movk_i32 s0, 0x3ff
	s_mov_b32 s11, 0
	s_waitcnt lgkmcnt(1)
	v_cmp_lt_i32_e32 vcc, s0, v2
	v_readfirstlane_b32 s18, v2
	s_waitcnt lgkmcnt(0)
	v_readfirstlane_b32 s17, v3
	s_cbranch_vccnz .LBB0_701
	s_lshl_b32 s0, s96, 3
	v_and_b32_e32 v12, 31, v0
	v_readlane_b32 s20, v238, 25
	s_and_b32 s0, s0, 0x1fffffe0
	s_ashr_i32 s19, s18, 31
	s_bfe_u32 s3, s20, 0x20006
	v_or_b32_e32 v90, s0, v12
	s_lshl_b64 s[0:1], s[18:19], 15
	s_add_u32 s0, s46, s0
	v_lshlrev_b32_e32 v2, 4, v0
	v_or_b32_e32 v6, 0x200, v0
	s_addc_u32 s1, s47, s1
	v_and_b32_e32 v54, 0xf0, v2
	v_lshrrev_b32_e32 v14, 4, v6
	v_lshl_add_u64 v[2:3], s[0:1], 0, v[54:55]
	v_lshlrev_b32_e32 v56, 8, v139
	v_mov_b32_e32 v57, v55
	v_lshlrev_b32_e32 v58, 8, v14
	v_mov_b32_e32 v59, v55
	s_lshl_b64 s[14:15], s[18:19], 14
	v_lshl_add_u64 v[4:5], v[2:3], 0, v[56:57]
	v_lshl_add_u64 v[6:7], v[2:3], 0, v[58:59]
	s_add_u32 s12, s48, 0x1000000
	global_load_dwordx4 v[18:21], v[4:5], off
	global_load_dwordx4 v[22:25], v[6:7], off
	v_or_b32_e32 v6, 0x600, v0
	s_addc_u32 s13, s49, 0
	s_lshl_b32 s10, s18, 4
	s_lshl_b32 s16, s18, 6
	v_lshrrev_b32_e32 v15, 4, v6
	v_or_b32_e32 v60, 0x4000, v56
	v_mov_b32_e32 v61, v55
	v_lshlrev_b32_e32 v62, 8, v15
	v_mov_b32_e32 v63, v55
	s_add_u32 s0, s48, s14
	v_lshl_add_u64 v[4:5], v[2:3], 0, v[60:61]
	v_lshl_add_u64 v[2:3], v[2:3], 0, v[62:63]
	s_addc_u32 s1, s49, s15
	s_and_b32 s10, s10, 0xfffff800
	global_load_dwordx4 v[26:29], v[4:5], off
	global_load_dwordx4 v[30:33], v[2:3], off
	v_lshl_add_u64 v[2:3], s[0:1], 0, v[54:55]
	s_add_u32 s0, s12, s14
	v_lshl_add_u64 v[4:5], v[2:3], 0, v[56:57]
	v_lshl_add_u64 v[2:3], v[2:3], 0, v[58:59]
	s_addc_u32 s1, s13, s15
	s_and_b32 s15, s20, 0xffffffc0
	global_load_dwordx4 v[34:37], v[4:5], off
	global_load_dwordx4 v[38:41], v[2:3], off
	v_or_b32_e32 v2, s15, v154
	v_mov_b32_e32 v3, v55
	s_and_b32 s14, s16, 0x7c0
	v_lshlrev_b64 v[2:3], 5, v[2:3]
	v_lshl_add_u64 v[4:5], s[0:1], 0, v[2:3]
	s_or_b32 s0, s10, s14
	global_load_dwordx4 v[50:53], v[4:5], off offset:16
	global_load_dwordx4 v[6:9], v[4:5], off
	v_add_u32_e32 v4, s0, v90
	v_ashrrev_i32_e32 v5, 31, v4
	v_lshlrev_b64 v[4:5], 12, v[4:5]
	s_lshl_b32 s0, s18, 3
	v_lshl_add_u64 v[4:5], s[56:57], 0, v[4:5]
	s_and_b32 s10, s0, 0x300
	v_lshrrev_b32_e32 v13, 5, v154
	v_lshl_add_u64 v[4:5], v[4:5], 0, s[10:11]
	s_lshl_b32 s10, s3, 6
	v_lshl_add_u64 v[4:5], v[4:5], 0, s[10:11]
	v_lshlrev_b32_e32 v10, 3, v13
	v_mov_b32_e32 v11, v55
	v_lshl_add_u64 v[4:5], v[4:5], 0, v[10:11]
	global_load_dwordx2 v[80:81], v[4:5], off offset:3072 nt
	global_load_dwordx2 v[78:79], v[4:5], off offset:3088 nt
	global_load_dwordx2 v[76:77], v[4:5], off offset:3104 nt
	global_load_dwordx2 v[70:71], v[4:5], off offset:3120 nt
	s_lshl_b32 s10, s3, 5
	s_lshl_b32 s0, s3, 2
	v_or_b32_e32 v10, s10, v12
	s_add_i32 s3, s0, 0
	s_movk_i32 s0, 0x110
	v_mul_u32_u24_e32 v10, 0x110, v10
	v_lshlrev_b32_e32 v11, 4, v13
	v_lshlrev_b32_e32 v4, 2, v13
	v_add3_u32 v91, 0, v10, v11
	v_mul_lo_u32 v10, v90, s0
	v_add3_u32 v92, 0, v10, v11
	v_or_b32_e32 v10, s10, v4
	v_readlane_b32 s68, v238, 29
	v_add_u32_e32 v5, 0, v54
	v_mul_u32_u24_e32 v11, 0x110, v139
	v_mul_u32_u24_e32 v12, 0x110, v14
	v_mul_u32_u24_e32 v13, 0x110, v15
	v_lshl_add_u64 v[64:65], s[46:47], 0, v[54:55]
	v_lshl_add_u64 v[66:67], s[48:49], 0, v[54:55]
	v_lshl_add_u64 v[68:69], s[12:13], 0, v[2:3]
	v_lshlrev_b32_e32 v54, 2, v10
	v_readlane_b32 s70, v238, 31
	v_readlane_b32 s71, v238, 32
	v_mbcnt_lo_u32_b32 v2, -1, 0
	v_cmp_gt_u32_e64 s[0:1], 32, v154
	v_lshlrev_b32_e32 v93, 4, v90
	v_lshl_add_u64 v[72:73], s[70:71], 0, v[54:55]
	v_add_u32_e32 v94, v5, v11
	v_add_u32_e32 v95, v5, v12
	v_add_u32_e32 v96, v5, v13
	s_lshl_b32 s12, s10, 1
	v_lshlrev_b32_e32 v74, 1, v4
	v_mbcnt_hi_u32_b32 v97, -1, v2
	v_mov_b32_e32 v98, 0x358637bd
	v_lshlrev_b32_e32 v54, 1, v10
	s_mov_b64 s[14:15], 0xc500400
	s_mov_b32 s19, 0xc500000
	v_mov_b32_e32 v99, v55
	v_readlane_b32 s69, v238, 30
	v_readlane_b32 s72, v238, 33
	v_readlane_b32 s73, v238, 34
	v_readlane_b32 s74, v238, 35
	v_readlane_b32 s75, v238, 36
	v_readlane_b32 s76, v238, 37
	v_readlane_b32 s77, v238, 38
	v_readlane_b32 s78, v238, 39
	v_readlane_b32 s79, v238, 40
	v_readlane_b32 s80, v238, 41
	v_readlane_b32 s81, v238, 42
	v_readlane_b32 s82, v238, 43
	v_readlane_b32 s83, v238, 44
	s_branch .LBB0_693

; __device__ __forceinline__ void hgC_loop(Frame& F, unsigned* ctr) {
;     ...
;         v2u ogc[4];
; #pragma unroll
;         for (int q = 0; q < 4; ++q) ogc[q] = og[q];
;         if (tid == 0) slot[par] = (int)__hip_atomic_fetch_add(ctr, 1u, __ATOMIC_RELAXED, __HIP_MEMORY_SCOPE_AGENT);
;         if (nxt < 1024) HGC_FETCH(nxt);
.LBB0_697:
	s_or_b64 exec, exec, s[20:21]
	s_cmpk_lt_i32 s16, 0x400
	s_cselect_b64 s[22:23], -1, 0
	s_cmpk_gt_i32 s16, 0x3ff
	s_cselect_b64 s[20:21], -1, 0
	s_waitcnt vmcnt(4)
	v_mov_b64_e32 v[48:49], v[8:9]
	v_mov_b64_e32 v[42:43], v[50:51]
	s_and_b64 vcc, exec, s[20:21]
	s_waitcnt vmcnt(0)
	v_mov_b64_e32 v[88:89], v[70:71]
	v_mov_b64_e32 v[86:87], v[76:77]
	v_mov_b64_e32 v[84:85], v[78:79]
	v_mov_b64_e32 v[82:83], v[80:81]
	v_mov_b64_e32 v[46:47], v[6:7]
	v_mov_b64_e32 v[44:45], v[52:53]
	s_cbranch_vccnz .LBB0_699
	s_ashr_i32 s17, s16, 31
	s_lshl_b64 s[24:25], s[16:17], 15
	v_lshl_add_u64 v[2:3], v[64:65], 0, s[24:25]
	v_lshl_add_u64 v[4:5], v[2:3], 0, v[56:57]
	s_lshl_b64 s[26:27], s[16:17], 14
	v_lshl_add_u64 v[10:11], v[2:3], 0, v[58:59]
	global_load_dwordx4 v[18:21], v[4:5], off
	global_load_dwordx4 v[22:25], v[10:11], off
	v_lshl_add_u64 v[4:5], v[2:3], 0, v[60:61]
	v_lshl_add_u64 v[2:3], v[2:3], 0, v[62:63]
	s_lshl_b32 s10, s16, 4
	s_lshl_b32 s13, s16, 6
	global_load_dwordx4 v[26:29], v[4:5], off
	global_load_dwordx4 v[30:33], v[2:3], off
	v_lshl_add_u64 v[2:3], v[66:67], 0, s[26:27]
	s_and_b32 s10, s10, 0xfffff800
	v_lshl_add_u64 v[4:5], v[2:3], 0, v[56:57]
	v_lshl_add_u64 v[2:3], v[2:3], 0, v[58:59]
	s_and_b32 s13, s13, 0x7c0
	global_load_dwordx4 v[34:37], v[4:5], off
	global_load_dwordx4 v[38:41], v[2:3], off
	v_lshl_add_u64 v[2:3], v[68:69], 0, s[26:27]
	s_or_b32 s10, s10, s13
	global_load_dwordx4 v[42:45], v[2:3], off offset:16
	global_load_dwordx4 v[46:49], v[2:3], off
	v_add_u32_e32 v2, s10, v90
	v_ashrrev_i32_e32 v3, 31, v2
	v_lshlrev_b64 v[2:3], 12, v[2:3]
	s_lshl_b32 s10, s16, 3
	v_lshl_add_u64 v[2:3], s[56:57], 0, v[2:3]
	s_and_b32 s10, s10, 0x300
	v_lshl_add_u64 v[2:3], v[2:3], 0, s[10:11]
	s_mov_b32 s13, s11
	v_lshl_add_u64 v[2:3], v[2:3], 0, s[12:13]
	v_mov_b32_e32 v75, v55
	v_lshl_add_u64 v[2:3], v[2:3], 0, v[74:75]
	global_load_dwordx2 v[82:83], v[2:3], off offset:3072 nt
	global_load_dwordx2 v[84:85], v[2:3], off offset:3088 nt
	global_load_dwordx2 v[86:87], v[2:3], off offset:3104 nt
	global_load_dwordx2 v[88:89], v[2:3], off offset:3120 nt
